# RG-LRU K-fragment gathers use SGPR base + 32-bit lane offset (saddr) instead of 64-bit lane addresses; slice select tests task-index bits directly
# baseline (speedup 1.0000x reference)
; #define LAS __attribute__((address_space(3)))
; __device__ __forceinline__ void lru_fused(const bf16* XC, const bf16* Wrg_t, const bf16* PROJ, bf16* YL, const float* b_a, const float* b_x, const float* sp8,
;                                           LAS unsigned char* lds, int tid, int lane, int wave, int vcu, int G) {
;     typedef pg8::bf16x8 bf16x8;
;     const int fr = lane & 15, fq = lane >> 4;
;     for (int vq = vcu; vq < 256; vq += G) {
;         const int h = vq >> 4, s = (vq >> 1) & 7, bsel = vq & 1;
;         __syncthreads();
;         { const int n = tid >> 3, p = tid & 7, chl = s * 32 + (n & 31), srow = h * 512 + (chl >> 7) * 256 + (n >> 5) * 128 + (chl & 127);
;           const v4u* src = (const v4u*)(Wrg_t + (size_t)srow * HD + p * 32); LAS v4u* dst = (LAS v4u*)(lds + n * RG_PITCH + p * 64);
; #pragma unroll
;           for (int q = 0; q < 4; ++q) dst[q] = src[q]; }
;         __syncthreads();
;         const int c0 = h * HD + s * 32;
;         f32x4 ba[2], bx[2], sp[2];
; #pragma unroll
;         for (int c2 = 0; c2 < 2; ++c2) { const int ch = c0 + 16 * c2 + 4 * fq; ba[c2] = *(const f32x4*)(b_a + ch); bx[c2] = *(const f32x4*)(b_x + ch); sp[c2] = *(const f32x4*)(sp8 + ch) * 1.44269504088896f; }
;         const bf16* abase = XC + h * HD + 8 * fq; const bf16* xbase = XC + c0 + 4 * fq; const bf16* gbase = PROJ + D + c0 + 4 * fq; bf16* obase = YL + c0 + 4 * fq;
;         const LAS unsigned char* bl = lds + fr * RG_PITCH + 16 * fq;
;         LAS float* xch = (LAS float*)(lds + LRU_XOFF);
;         bf16x8 af[2][8]; v2u xq[2][2], gq[2][2];
;         { const size_t row0 = (size_t)bsel * SEQ + (size_t)wave * 32;
; #pragma unroll
;           for (int r2 = 0; r2 < 2; ++r2) { const size_t ro = (row0 + 16 * r2 + fr) * D, rg = (row0 + 16 * r2 + fr) * NIN;
; #pragma unroll
;               for (int kb = 0; kb < 8; ++kb) af[r2][kb] = *(const bf16x8*)(abase + ro + 32 * kb);
; #pragma unroll
;               for (int c2 = 0; c2 < 2; ++c2) { xq[r2][c2] = *(const v2u*)(xbase + ro + 16 * c2); gq[r2][c2] = *(const v2u*)(gbase + rg + 16 * c2); } } }
.LBB0_450:
	s_add_u32 s0, s12, 0x46e00000
	s_addc_u32 s1, s13, 0
	s_add_u32 s4, s12, 0x46e10000
	s_addc_u32 s5, s13, 0
	s_cmp_lt_i32 s28, 5
	s_cselect_b64 s[2:3], -1, 0
	s_cmp_gt_i32 s29, 4
	s_cselect_b64 s[6:7], -1, 0
	s_and_b64 s[2:3], s[2:3], s[6:7]
	s_mov_b64 s[78:79], s[12:13]
	s_andn2_b64 vcc, exec, s[2:3]
	s_cbranch_vccnz .LBB0_537
	s_cmpk_gt_i32 s34, 0xff
	s_cbranch_scc1 .LBB0_478
	s_waitcnt vmcnt(0)
	v_and_b32_e32 v2, 7, v0
	v_lshlrev_b32_e32 v4, 6, v2
	v_mov_b32_e32 v2, 0
	v_readlane_b32 s2, v249, 25
	v_mov_b32_e32 v5, v2
	v_readlane_b32 s3, v249, 26
	v_lshrrev_b32_e32 v3, 4, v178
	v_lshrrev_b32_e32 v6, 3, v0
	v_lshl_add_u64 v[112:113], s[2:3], 0, v[4:5]
	s_movk_i32 s6, 0x220
	v_readlane_b32 s2, v249, 35
	v_mad_u32_u24 v5, v6, s6, 0
	v_lshlrev_b32_e32 v6, 4, v3
	v_mov_b32_e32 v7, v2
	v_and_b32_e32 v8, 48, v178
	v_mov_b32_e32 v9, v2
	v_readlane_b32 s3, v249, 36
	s_mov_b64 s[16:17], s[78:79]
	v_and_b32_e32 v110, 15, v0
	v_lshl_add_u64 v[114:115], s[2:3], 0, v[8:9]
	v_lshl_add_u64 v[116:117], s[2:3], 0, v[6:7]
	s_mov_b64 s[68:69], s[2:3]
	v_lshl_add_u64 v[6:7], s[16:17], 0, v[6:7]
	s_mov_b64 s[2:3], 0x18e02000
	v_lshl_add_u64 v[118:119], v[6:7], 0, s[2:3]
	v_readlane_b32 s2, v249, 38
	v_lshlrev_b32_e32 v165, 2, v3
	v_and_b32_e32 v3, 12, v110
	v_lshlrev_b32_e32 v3, 1, v3
	v_and_or_b32 v3, v110, 3, v3
	v_mad_u32_u24 v3, v3, s6, 0
	s_mov_b32 s8, s2
	s_lshl_b32 s6, s2, 5
	s_cmp_eq_u32 s8, 7
	s_cselect_b64 s[12:13], -1, 0
	v_cmp_eq_u32_e32 vcc, 0, v110
	s_and_b64 s[40:41], vcc, s[12:13]
	v_readlane_b32 s7, v249, 37
	s_cmp_gt_u32 s7, 63
	s_cselect_b64 s[42:43], -1, 0
	s_cmpk_gt_u32 s7, 0x7f
	s_cselect_b64 s[44:45], -1, 0
	s_cmpk_gt_u32 s7, 0xbf
	v_and_b32_e32 v9, 48, v0
	s_cselect_b64 s[48:49], -1, 0
	s_cmpk_gt_u32 s7, 0xff
	s_cselect_b64 s[50:51], -1, 0
	s_cmpk_gt_u32 s7, 0x13f
	v_add_u32_e32 v170, v3, v9
	v_mbcnt_lo_u32_b32 v3, -1, 0
	v_lshrrev_b32_e32 v10, 1, v0
	s_cselect_b64 s[52:53], -1, 0
	s_cmpk_gt_u32 s7, 0x17f
	v_mbcnt_hi_u32_b32 v3, -1, v3
	v_readlane_b32 s3, v249, 39
	v_or_b32_e32 v166, s6, v110
	v_readlane_b32 s36, v249, 31
	s_cselect_b64 s[54:55], -1, 0
	s_cmpk_gt_u32 s7, 0x1bf
	v_and_b32_e32 v6, 48, v0
	v_mov_b32_e32 v7, v2
	v_and_or_b32 v3, v3, 64, v178
	v_bfe_u32 v1, v0, 3, 5
	v_and_b32_e32 v164, 0x80, v10
	s_mov_b32 s39, 0
	v_mov_b32_e32 v111, v2
	v_add_u32_e32 v167, 0, v8
	v_cmp_eq_u32_e64 s[2:3], 15, v110
	v_readlane_b32 s37, v249, 32
	s_cselect_b64 s[58:59], -1, 0
	v_lshl_add_u64 v[120:121], s[16:17], 0, v[6:7]
	v_or_b32_e32 v168, 16, v166
	s_lshl_b32 s7, s34, 13
	s_lshl_b32 s8, s10, 13
	s_lshl_b32 s11, s34, 4
	s_lshl_b32 s12, s10, 4
	v_add_u32_e32 v169, v5, v4
	s_mov_b32 s62, 0x3fb8aa3b
	s_mov_b32 s13, 0xa000
	s_mov_b32 s16, 0xa0000
	v_mov_b32_e32 v171, 0xc0135761
	s_mov_b32 s17, 0x50e00000
	v_lshl_or_b32 v172, v3, 2, 60
	s_mov_b32 s18, s34
	s_branch .LBB0_454

; #define LAS __attribute__((address_space(3)))
; __device__ __forceinline__ void lru_fused(const bf16* XC, const bf16* Wrg_t, const bf16* PROJ, bf16* YL, const float* b_a, const float* b_x, const float* sp8,
;                                           LAS unsigned char* lds, int tid, int lane, int wave, int vcu, int G) {
;     ...
;                 bf16x8 bq[2][4];
; #pragma unroll
;                 for (int cb = 0; cb < 4; ++cb) bq[0][cb] = *(const LAS bf16x8*)(bl + cb * 16 * RG_PITCH);
; #pragma unroll
;                 for (int kb = 0; kb < 8; ++kb) {
;                     if (kb + 1 < 8) {
; #pragma unroll
;                         for (int cb = 0; cb < 4; ++cb) bq[(kb + 1) & 1][cb] = *(const LAS bf16x8*)(bl + cb * 16 * RG_PITCH + (kb + 1) * 64); }
;                     __builtin_amdgcn_sched_barrier(0);
.LBB0_456:
	ds_read_b128 v[86:89], v170
	ds_read_b128 v[90:93], v170 offset:64
	ds_read_b128 v[94:97], v170 offset:2176
	ds_read_b128 v[98:101], v170 offset:2240
	ds_read_b128 v[106:109], v170 offset:17408
	ds_read_b128 v[154:157], v170 offset:17472
	ds_read_b128 v[160:163], v170 offset:19584
	ds_read_b128 v[174:177], v170 offset:19648
	s_waitcnt vmcnt(15)
	s_waitcnt vmcnt(12)
	s_waitcnt vmcnt(3)
	s_waitcnt vmcnt(1)
	s_bitcmp0_b32 s18, 3
	s_cbranch_scc0 .Lxq_4567
	s_bitcmp0_b32 s18, 2
	s_cbranch_scc0 .Lxq_23
	s_bitcmp0_b32 s18, 1
	s_cbranch_scc0 .Lxq_1
	v_mov_b64_e32 v[198:199], v[70:71]
	v_mov_b64_e32 v[104:105], v[72:73]
	v_mov_b64_e32 v[102:103], v[82:83]
	v_mov_b64_e32 v[4:5], v[84:85]
	s_branch .Lxq_done

; __device__ __forceinline__ float bf_lo(unsigned w) { return __uint_as_float(w << 16); }
; __device__ __forceinline__ float bf_hi(unsigned w) { return __uint_as_float(w & 0xffff0000u); }
; __device__ __forceinline__ void lru_fused(const bf16* XC, const bf16* Wrg_t, const bf16* PROJ, bf16* YL, const float* b_a, const float* b_x, const float* sp8,
;                                           LAS unsigned char* lds, int tid, int lane, int wave, int vcu, int G) {
;     ...
; #pragma unroll
;             for (int r2 = 0; r2 < 2; ++r2)
; #pragma unroll
;                 for (int c2 = 0; c2 < 2; ++c2) { const f32x4 rp = acc[r2][c2] + ba[c2], ip = acc[r2][c2 + 2] + bx[c2]; const v2u xw = xq[r2][c2];
;                     const float xv[4] = {bf_lo(xw.x), bf_hi(xw.x), bf_lo(xw.y), bf_hi(xw.y)};
.Lxq_23:
	s_bitcmp0_b32 s18, 1
	s_cbranch_scc0 .Lxq_3
	v_mov_b64_e32 v[198:199], v[54:55]
	v_mov_b64_e32 v[104:105], v[56:57]
	v_mov_b64_e32 v[102:103], v[74:75]
	v_mov_b64_e32 v[4:5], v[76:77]
	s_branch .Lxq_done

; __device__ __forceinline__ float bf_lo(unsigned w) { return __uint_as_float(w << 16); }
; __device__ __forceinline__ float bf_hi(unsigned w) { return __uint_as_float(w & 0xffff0000u); }
; __device__ __forceinline__ void lru_fused(const bf16* XC, const bf16* Wrg_t, const bf16* PROJ, bf16* YL, const float* b_a, const float* b_x, const float* sp8,
;                                           LAS unsigned char* lds, int tid, int lane, int wave, int vcu, int G) {
;     ...
; #pragma unroll
;             for (int r2 = 0; r2 < 2; ++r2)
; #pragma unroll
;                 for (int c2 = 0; c2 < 2; ++c2) { const f32x4 rp = acc[r2][c2] + ba[c2], ip = acc[r2][c2 + 2] + bx[c2]; const v2u xw = xq[r2][c2];
;                     const float xv[4] = {bf_lo(xw.x), bf_hi(xw.x), bf_lo(xw.y), bf_hi(xw.y)};
.Lxq_4567:
	s_bitcmp0_b32 s18, 2
	s_cbranch_scc0 .Lxq_67
	s_bitcmp0_b32 s18, 1
	s_cbranch_scc0 .Lxq_5
	v_mov_b64_e32 v[198:199], v[34:35]
	v_mov_b64_e32 v[104:105], v[36:37]
	v_mov_b64_e32 v[102:103], v[58:59]
	v_mov_b64_e32 v[4:5], v[60:61]
	s_branch .Lxq_done

; __device__ __forceinline__ float bf_lo(unsigned w) { return __uint_as_float(w << 16); }
; __device__ __forceinline__ float bf_hi(unsigned w) { return __uint_as_float(w & 0xffff0000u); }
; __device__ __forceinline__ void lru_fused(const bf16* XC, const bf16* Wrg_t, const bf16* PROJ, bf16* YL, const float* b_a, const float* b_x, const float* sp8,
;                                           LAS unsigned char* lds, int tid, int lane, int wave, int vcu, int G) {
;     ...
; #pragma unroll
;             for (int r2 = 0; r2 < 2; ++r2)
; #pragma unroll
;                 for (int c2 = 0; c2 < 2; ++c2) { const f32x4 rp = acc[r2][c2] + ba[c2], ip = acc[r2][c2 + 2] + bx[c2]; const v2u xw = xq[r2][c2];
;                     const float xv[4] = {bf_lo(xw.x), bf_hi(xw.x), bf_lo(xw.y), bf_hi(xw.y)};
.Lxq_67:
	s_bitcmp0_b32 s18, 1
	s_cbranch_scc0 .Lxq_7
	v_mov_b64_e32 v[198:199], v[26:27]
	v_mov_b64_e32 v[104:105], v[28:29]
	v_mov_b64_e32 v[102:103], v[42:43]
	v_mov_b64_e32 v[4:5], v[44:45]
	s_branch .Lxq_done

; #define LAS __attribute__((address_space(3)))
; __device__ __forceinline__ void lru_fused(const bf16* XC, const bf16* Wrg_t, const bf16* PROJ, bf16* YL, const float* b_a, const float* b_x, const float* sp8,
;                                           LAS unsigned char* lds, int tid, int lane, int wave, int vcu, int G) {
;     ...
;                 for (int kb = 0; kb < 8; ++kb) {
;                     if (kb + 1 < 8) {
; #pragma unroll
;                         for (int cb = 0; cb < 4; ++cb) bq[(kb + 1) & 1][cb] = *(const LAS bf16x8*)(bl + cb * 16 * RG_PITCH + (kb + 1) * 64); }
;                     __builtin_amdgcn_sched_barrier(0);
; #pragma unroll
;                     for (int cb = 0; cb < 4; ++cb)
; #pragma unroll
;                         for (int r2 = 0; r2 < 2; ++r2) acc[r2][cb] = __builtin_amdgcn_mfma_f32_16x16x32_bf16(bq[kb & 1][cb], af[r2][kb], acc[r2][cb], 0, 0, 0);
;                     __builtin_amdgcn_sched_barrier(0);
;                 }
.Lxq_done:
	s_waitcnt lgkmcnt(7)
	v_mfma_f32_16x16x32_bf16 v[142:145], v[86:89], v[70:73], 0
	v_mfma_f32_16x16x32_bf16 v[86:89], v[86:89], v[82:85], 0
	s_waitcnt lgkmcnt(5)
	v_mfma_f32_16x16x32_bf16 v[148:151], v[94:97], v[70:73], 0
	v_mfma_f32_16x16x32_bf16 v[94:97], v[94:97], v[82:85], 0
	s_waitcnt lgkmcnt(3)
	v_mfma_f32_16x16x32_bf16 v[182:185], v[106:109], v[70:73], 0
	v_mfma_f32_16x16x32_bf16 v[106:109], v[106:109], v[82:85], 0
	s_waitcnt lgkmcnt(1)
	v_mfma_f32_16x16x32_bf16 v[70:73], v[160:163], v[70:73], 0
	v_mfma_f32_16x16x32_bf16 v[82:85], v[160:163], v[82:85], 0
	ds_read_b128 v[160:163], v170 offset:128
	ds_read_b128 v[186:189], v170 offset:2304
	ds_read_b128 v[190:193], v170 offset:17536
	ds_read_b128 v[194:197], v170 offset:19712
	v_mfma_f32_16x16x32_bf16 v[142:145], v[90:93], v[62:65], v[142:145]
	v_mfma_f32_16x16x32_bf16 v[86:89], v[90:93], v[78:81], v[86:89]
	v_mfma_f32_16x16x32_bf16 v[90:93], v[98:101], v[62:65], v[148:151]
	v_mfma_f32_16x16x32_bf16 v[94:97], v[98:101], v[78:81], v[94:97]
	v_mfma_f32_16x16x32_bf16 v[98:101], v[154:157], v[62:65], v[182:185]
	s_waitcnt lgkmcnt(4)
	v_mfma_f32_16x16x32_bf16 v[62:65], v[174:177], v[62:65], v[70:73]
	v_mfma_f32_16x16x32_bf16 v[70:73], v[174:177], v[78:81], v[82:85]
	v_mfma_f32_16x16x32_bf16 v[106:109], v[154:157], v[78:81], v[106:109]
	ds_read_b128 v[78:81], v170 offset:192
	s_nop 0
	ds_read_b128 v[82:85], v170 offset:2368
	ds_read_b128 v[148:151], v170 offset:17600
	ds_read_b128 v[154:157], v170 offset:19776
	s_waitcnt lgkmcnt(7)
	v_mfma_f32_16x16x32_bf16 v[142:145], v[160:163], v[54:57], v[142:145]
	v_mfma_f32_16x16x32_bf16 v[86:89], v[160:163], v[74:77], v[86:89]
	s_waitcnt lgkmcnt(6)
	v_mfma_f32_16x16x32_bf16 v[90:93], v[186:189], v[54:57], v[90:93]
	v_mfma_f32_16x16x32_bf16 v[94:97], v[186:189], v[74:77], v[94:97]
	s_waitcnt lgkmcnt(5)
	v_mfma_f32_16x16x32_bf16 v[98:101], v[190:193], v[54:57], v[98:101]
	s_waitcnt lgkmcnt(4)
	v_mfma_f32_16x16x32_bf16 v[54:57], v[194:197], v[54:57], v[62:65]
	v_mfma_f32_16x16x32_bf16 v[62:65], v[194:197], v[74:77], v[70:73]
	v_mfma_f32_16x16x32_bf16 v[106:109], v[190:193], v[74:77], v[106:109]
	s_nop 1
	ds_read_b128 v[70:73], v170 offset:256
	ds_read_b128 v[74:77], v170 offset:2432
	ds_read_b128 v[160:163], v170 offset:17664
	ds_read_b128 v[174:177], v170 offset:19840
	s_waitcnt lgkmcnt(7)
	v_mfma_f32_16x16x32_bf16 v[142:145], v[78:81], v[46:49], v[142:145]
	v_mfma_f32_16x16x32_bf16 v[78:81], v[78:81], v[66:69], v[86:89]
	s_waitcnt lgkmcnt(6)
	v_mfma_f32_16x16x32_bf16 v[86:89], v[82:85], v[46:49], v[90:93]
	v_mfma_f32_16x16x32_bf16 v[82:85], v[82:85], v[66:69], v[94:97]
	s_waitcnt lgkmcnt(5)
	v_mfma_f32_16x16x32_bf16 v[90:93], v[148:151], v[46:49], v[98:101]
	v_mfma_f32_16x16x32_bf16 v[94:97], v[148:151], v[66:69], v[106:109]
	s_waitcnt lgkmcnt(4)
	v_mfma_f32_16x16x32_bf16 v[46:49], v[154:157], v[46:49], v[54:57]
	v_mfma_f32_16x16x32_bf16 v[54:57], v[154:157], v[66:69], v[62:65]
	s_nop 2
	ds_read_b128 v[62:65], v170 offset:320
	ds_read_b128 v[66:69], v170 offset:2496
	ds_read_b128 v[98:101], v170 offset:17728
	ds_read_b128 v[106:109], v170 offset:19904
	s_waitcnt lgkmcnt(7)
	v_mfma_f32_16x16x32_bf16 v[142:145], v[70:73], v[34:37], v[142:145]
	v_mfma_f32_16x16x32_bf16 v[70:73], v[70:73], v[58:61], v[78:81]
	s_waitcnt lgkmcnt(6)
	v_mfma_f32_16x16x32_bf16 v[78:81], v[74:77], v[34:37], v[86:89]
	v_mfma_f32_16x16x32_bf16 v[74:77], v[74:77], v[58:61], v[82:85]
	s_waitcnt lgkmcnt(5)
	v_mfma_f32_16x16x32_bf16 v[82:85], v[160:163], v[34:37], v[90:93]
	v_mfma_f32_16x16x32_bf16 v[86:89], v[160:163], v[58:61], v[94:97]
	s_waitcnt lgkmcnt(4)
	v_mfma_f32_16x16x32_bf16 v[34:37], v[174:177], v[34:37], v[46:49]
	v_mfma_f32_16x16x32_bf16 v[46:49], v[174:177], v[58:61], v[54:57]
	s_nop 2
	ds_read_b128 v[54:57], v170 offset:384
	ds_read_b128 v[58:61], v170 offset:2560
	ds_read_b128 v[90:93], v170 offset:17792
	ds_read_b128 v[94:97], v170 offset:19968
	s_waitcnt lgkmcnt(7)
	v_mfma_f32_16x16x32_bf16 v[142:145], v[62:65], v[30:33], v[142:145]
	v_mfma_f32_16x16x32_bf16 v[62:65], v[62:65], v[50:53], v[70:73]
	s_waitcnt lgkmcnt(6)
	v_mfma_f32_16x16x32_bf16 v[70:73], v[66:69], v[30:33], v[78:81]
	v_mfma_f32_16x16x32_bf16 v[66:69], v[66:69], v[50:53], v[74:77]
	s_waitcnt lgkmcnt(5)
	v_mfma_f32_16x16x32_bf16 v[74:77], v[98:101], v[30:33], v[82:85]
	v_mfma_f32_16x16x32_bf16 v[78:81], v[98:101], v[50:53], v[86:89]
	s_waitcnt lgkmcnt(4)
	v_mfma_f32_16x16x32_bf16 v[30:33], v[106:109], v[30:33], v[34:37]
	v_mfma_f32_16x16x32_bf16 v[34:37], v[106:109], v[50:53], v[46:49]
	s_nop 2
	ds_read_b128 v[46:49], v170 offset:448
	ds_read_b128 v[50:53], v170 offset:2624
	ds_read_b128 v[82:85], v170 offset:17856
	ds_read_b128 v[86:89], v170 offset:20032
	s_waitcnt lgkmcnt(7)
	v_mfma_f32_16x16x32_bf16 v[98:101], v[54:57], v[26:29], v[142:145]
	v_mfma_f32_16x16x32_bf16 v[54:57], v[54:57], v[42:45], v[62:65]
	s_waitcnt lgkmcnt(6)
	v_mfma_f32_16x16x32_bf16 v[62:65], v[58:61], v[26:29], v[70:73]
	v_mfma_f32_16x16x32_bf16 v[58:61], v[58:61], v[42:45], v[66:69]
	s_waitcnt lgkmcnt(5)
	v_mfma_f32_16x16x32_bf16 v[66:69], v[90:93], v[26:29], v[74:77]
	v_mfma_f32_16x16x32_bf16 v[70:73], v[90:93], v[42:45], v[78:81]
	s_waitcnt lgkmcnt(4)
	v_mfma_f32_16x16x32_bf16 v[26:29], v[94:97], v[26:29], v[30:33]
	v_mfma_f32_16x16x32_bf16 v[30:33], v[94:97], v[42:45], v[34:37]
	s_waitcnt lgkmcnt(3)
	v_mfma_f32_16x16x32_bf16 v[106:109], v[46:49], v[22:25], v[98:101]
	v_mfma_f32_16x16x32_bf16 v[98:101], v[46:49], v[38:41], v[54:57]
	s_waitcnt lgkmcnt(2)
	v_mfma_f32_16x16x32_bf16 v[188:191], v[50:53], v[22:25], v[62:65]
	v_mfma_f32_16x16x32_bf16 v[90:93], v[50:53], v[38:41], v[58:61]
	s_waitcnt lgkmcnt(1)
; __device__ __forceinline__ float bf_lo(unsigned w) { return __uint_as_float(w << 16); }
; __device__ __forceinline__ float bf_hi(unsigned w) { return __uint_as_float(w & 0xffff0000u); }
; __device__ __forceinline__ float sigmoidf_(float x) { return fast_rcp(1.0f + fast_exp(-x)); }
; __device__ __forceinline__ void lru_fused(const bf16* XC, const bf16* Wrg_t, const bf16* PROJ, bf16* YL, const float* b_a, const float* b_x, const float* sp8,
;                                           LAS unsigned char* lds, int tid, int lane, int wave, int vcu, int G) {
;     ...
;             { const size_t rown = (i + 1 < SEQ / 256) ? row0 + 256 : row0;
; #pragma unroll
;                 for (int r2 = 0; r2 < 2; ++r2) { const size_t ro = (rown + 16 * r2 + fr) * D, rg = (rown + 16 * r2 + fr) * NIN;
; #pragma unroll
;                     for (int kb = 0; kb < 8; ++kb) af[r2][kb] = *(const bf16x8*)(abase + ro + 32 * kb);
; #pragma unroll
;                     for (int c2 = 0; c2 < 2; ++c2) { xqn[r2][c2] = *(const v2u*)(xbase + ro + 16 * c2); gqn[r2][c2] = *(const v2u*)(gbase + rg + 16 * c2); } } }
;             float A[2][2][4], U[2][2][4];
; #pragma unroll
;             for (int r2 = 0; r2 < 2; ++r2)
; #pragma unroll
;                 for (int c2 = 0; c2 < 2; ++c2) { const f32x4 rp = acc[r2][c2] + ba[c2], ip = acc[r2][c2 + 2] + bx[c2]; const v2u xw = xq[r2][c2];
;                     const float xv[4] = {bf_lo(xw.x), bf_hi(xw.x), bf_lo(xw.y), bf_hi(xw.y)};
; #pragma unroll
;                     for (int j = 0; j < 4; ++j) { const float r = pg8::sigmoidf_(rp[j]), ig = pg8::sigmoidf_(ip[j]);
;                         const float av = __builtin_amdgcn_exp2f(sp[c2][j] * r);
;                         A[r2][c2][j] = av; U[r2][c2][j] = __builtin_amdgcn_sqrtf(fmaxf(__builtin_fmaf(-av, av, 1.0f), 0.0f)) * (ig * xv[j]); } }
	v_mfma_f32_16x16x32_bf16 v[182:185], v[82:85], v[22:25], v[66:69]
	v_mfma_f32_16x16x32_bf16 v[94:97], v[82:85], v[38:41], v[70:73]
	s_waitcnt lgkmcnt(0)
	v_mfma_f32_16x16x32_bf16 v[192:195], v[86:89], v[22:25], v[26:29]
	v_mfma_f32_16x16x32_bf16 v[86:89], v[86:89], v[38:41], v[30:33]
	v_add_f32_e32 v3, v6, v106
	v_mul_f32_e32 v3, 0xbfb8aa3b, v3
	v_exp_f32_e32 v3, v3
	s_add_u32 s23, s19, 0xffffff00
	s_addc_u32 s24, s20, -1
	s_cmp_eq_u32 s64, 0x3e00000
	s_cselect_b32 s25, s24, s20
	s_cselect_b32 s24, s23, s19
	v_mov_b32_e32 v39, s25
	v_or_b32_e32 v38, s24, v110
	v_lshlrev_b64 v[40:41], 13, v[38:39]
	v_mad_u64_u32 v[38:39], s[26:27], v38, s13, v[126:127]
	s_mul_i32 s23, s25, 0xa000
	v_lshl_add_u64 v[22:23], v[122:123], 0, v[40:41]
	v_subrev_u32_e32 v22, s68, v22
	v_lshl_add_u64 v[40:41], v[124:125], 0, v[40:41]
	v_add_u32_e32 v39, s23, v39
	global_load_dwordx4 v[70:73], v22, s[68:69]
	s_nop 0
	v_add_f32_e32 v173, v14, v182
	v_mul_f32_e32 v173, 0xbfb8aa3b, v173
	v_exp_f32_e32 v174, v173
	v_add_f32_e32 v3, 1.0, v3
	v_rcp_f32_e32 v3, v3
	v_add_f32_e32 v107, v7, v107
	v_add_f32_e32 v174, 1.0, v174
	v_mul_f32_e32 v107, 0xbfb8aa3b, v107
	v_mul_f32_e32 v3, v134, v3
	v_exp_f32_e32 v173, v3
	v_rcp_f32_e32 v174, v174
	v_exp_f32_e32 v107, v107
	v_lshlrev_b32_e32 v106, 16, v198
	v_fma_f32 v175, -v173, v173, 1.0
	global_load_dwordx4 v[62:65], v22, s[68:69] offset:64
	v_mul_f32_e32 v106, v174, v106
	v_add_f32_e32 v174, v15, v183
	v_add_f32_e32 v107, 1.0, v107
	v_max_f32_e32 v175, 0, v175
	v_mul_f32_e32 v174, 0xbfb8aa3b, v174
	v_rcp_f32_e32 v107, v107
	v_sqrt_f32_e32 v175, v175
	v_exp_f32_e32 v174, v174
	v_add_f32_e32 v177, v16, v184
	v_mul_f32_e32 v107, v135, v107
	v_mul_f32_e32 v175, v106, v175
	v_add_f32_e32 v106, 1.0, v174
	v_exp_f32_e32 v174, v107
	v_add_f32_e32 v107, v8, v108
	v_mul_f32_e32 v107, 0xbfb8aa3b, v107
	v_exp_f32_e32 v107, v107
	global_load_dwordx4 v[54:57], v22, s[68:69] offset:128
	v_fma_f32 v108, -v174, v174, 1.0
	v_rcp_f32_e32 v106, v106
	v_max_f32_e32 v108, 0, v108
	v_add_f32_e32 v107, 1.0, v107
	v_mul_f32_e32 v177, 0xbfb8aa3b, v177
	v_rcp_f32_e32 v107, v107
	v_sqrt_f32_e32 v108, v108
	v_exp_f32_e32 v181, v177
	v_and_b32_e32 v176, 0xffff0000, v198
	v_mul_f32_e32 v106, v106, v176
	v_mul_f32_e32 v107, v132, v107
	v_mul_f32_e32 v177, v106, v108
	v_add_f32_e32 v106, 1.0, v181
	v_exp_f32_e32 v181, v107
	v_add_f32_e32 v107, v9, v109
	global_load_dwordx4 v[46:49], v22, s[68:69] offset:192
	v_mul_f32_e32 v107, 0xbfb8aa3b, v107
	v_exp_f32_e32 v107, v107
	v_add_f32_e32 v109, v17, v185
	v_mul_f32_e32 v109, 0xbfb8aa3b, v109
	v_exp_f32_e32 v109, v109
	v_add_f32_e32 v107, 1.0, v107
	v_rcp_f32_e32 v107, v107
	v_fma_f32 v108, -v181, v181, 1.0
	v_max_f32_e32 v108, 0, v108
	v_and_b32_e32 v3, 0xffff0000, v199
	v_mul_f32_e32 v107, v133, v107
	v_exp_f32_e32 v176, v107
	v_sqrt_f32_e32 v107, v108
	v_add_f32_e32 v108, 1.0, v109
	v_rcp_f32_e32 v108, v108
	global_load_dwordx4 v[34:37], v22, s[68:69] offset:256
	v_fma_f32 v109, -v176, v176, 1.0
	v_max_f32_e32 v109, 0, v109
	v_sqrt_f32_e32 v109, v109
	v_mul_f32_e32 v3, v108, v3
	v_add_f32_e32 v108, v18, v192
	v_rcp_f32_e32 v106, v106
	v_mul_f32_e32 v182, v3, v109
	v_add_f32_e32 v3, v10, v188
	v_mul_f32_e32 v3, 0xbfb8aa3b, v3
	v_exp_f32_e32 v3, v3
	v_mul_f32_e32 v108, 0xbfb8aa3b, v108
	v_exp_f32_e32 v108, v108
	v_lshlrev_b32_e32 v186, 16, v199
	v_add_f32_e32 v3, 1.0, v3
	v_rcp_f32_e32 v3, v3
	v_mul_f32_e32 v106, v106, v186
	global_load_dwordx4 v[30:33], v22, s[68:69] offset:320
	v_mul_f32_e32 v184, v106, v107
	v_lshlrev_b32_e32 v107, 16, v105
	v_mul_f32_e32 v3, v138, v3
	v_exp_f32_e32 v183, v3
	v_and_b32_e32 v3, 0xffff0000, v105
	v_add_f32_e32 v105, 1.0, v108
	v_rcp_f32_e32 v105, v105
	v_lshlrev_b32_e32 v106, 16, v104
	v_fma_f32 v108, -v183, v183, 1.0
	v_add_f32_e32 v109, v19, v193
	v_mul_f32_e32 v105, v105, v106
	v_add_f32_e32 v106, v11, v189
	v_mul_f32_e32 v106, 0xbfb8aa3b, v106
	v_exp_f32_e32 v106, v106
	v_max_f32_e32 v108, 0, v108
	global_load_dwordx4 v[26:29], v22, s[68:69] offset:384
	v_mul_f32_e32 v109, 0xbfb8aa3b, v109
	v_sqrt_f32_e32 v108, v108
	v_add_f32_e32 v106, 1.0, v106
	v_rcp_f32_e32 v106, v106
	v_exp_f32_e32 v109, v109
	v_mul_f32_e32 v186, v105, v108
	v_and_b32_e32 v104, 0xffff0000, v104
	v_mul_f32_e32 v106, v139, v106
	v_exp_f32_e32 v185, v106
	v_add_f32_e32 v106, v12, v190
	v_mul_f32_e32 v106, 0xbfb8aa3b, v106
	v_exp_f32_e32 v106, v106
	v_add_f32_e32 v105, 1.0, v109
	v_rcp_f32_e32 v105, v105
	v_fma_f32 v108, -v185, v185, 1.0
	s_nop 0
	global_load_dwordx4 v[22:25], v22, s[68:69] offset:448
	v_add_f32_e32 v106, 1.0, v106
	v_rcp_f32_e32 v106, v106
	v_mul_f32_e32 v104, v105, v104
	v_max_f32_e32 v108, 0, v108
	v_sqrt_f32_e32 v108, v108
	v_mul_f32_e32 v105, v136, v106
	v_exp_f32_e32 v189, v105
	v_add_f32_e32 v105, v13, v191
	v_mul_f32_e32 v105, 0xbfb8aa3b, v105
	v_exp_f32_e32 v105, v105
	v_mul_f32_e32 v188, v104, v108
	v_add_f32_e32 v108, v21, v195
	v_mul_f32_e32 v108, 0xbfb8aa3b, v108
	v_add_f32_e32 v105, 1.0, v105
	v_rcp_f32_e32 v105, v105
	s_nop 0
	v_exp_f32_e32 v108, v108
	v_fma_f32 v106, -v189, v189, 1.0
	v_max_f32_e32 v106, 0, v106
	v_mul_f32_e32 v105, v137, v105
	v_exp_f32_e32 v187, v105
	v_sqrt_f32_e32 v105, v106
	v_add_f32_e32 v106, 1.0, v108
	v_rcp_f32_e32 v106, v106
	v_fma_f32 v108, -v187, v187, 1.0
	v_max_f32_e32 v108, 0, v108
	v_sqrt_f32_e32 v108, v108
	v_mul_f32_e32 v3, v106, v3
	v_add_f32_e32 v109, v20, v194
	v_mul_f32_e32 v109, 0xbfb8aa3b, v109
	v_mul_f32_e32 v190, v3, v108
	v_add_f32_e32 v3, v6, v98
	v_mul_f32_e32 v3, 0xbfb8aa3b, v3
	v_exp_f32_e32 v3, v3
	v_exp_f32_e32 v109, v109
	v_add_f32_e32 v99, v7, v99
	v_mul_f32_e32 v99, 0xbfb8aa3b, v99
	v_add_f32_e32 v3, 1.0, v3
; __device__ __forceinline__ float bf_lo(unsigned w) { return __uint_as_float(w << 16); }
; __device__ __forceinline__ float bf_hi(unsigned w) { return __uint_as_float(w & 0xffff0000u); }
; __device__ __forceinline__ float sigmoidf_(float x) { return fast_rcp(1.0f + fast_exp(-x)); }
; __device__ __forceinline__ void lru_fused(const bf16* XC, const bf16* Wrg_t, const bf16* PROJ, bf16* YL, const float* b_a, const float* b_x, const float* sp8,
;                                           LAS unsigned char* lds, int tid, int lane, int wave, int vcu, int G) {
;     ...
;             { const size_t rown = (i + 1 < SEQ / 256) ? row0 + 256 : row0;
; #pragma unroll
;                 for (int r2 = 0; r2 < 2; ++r2) { const size_t ro = (rown + 16 * r2 + fr) * D, rg = (rown + 16 * r2 + fr) * NIN;
; #pragma unroll
;                     for (int kb = 0; kb < 8; ++kb) af[r2][kb] = *(const bf16x8*)(abase + ro + 32 * kb);
; #pragma unroll
;                     for (int c2 = 0; c2 < 2; ++c2) { xqn[r2][c2] = *(const v2u*)(xbase + ro + 16 * c2); gqn[r2][c2] = *(const v2u*)(gbase + rg + 16 * c2); } } }
;             float A[2][2][4], U[2][2][4];
; #pragma unroll
;             for (int r2 = 0; r2 < 2; ++r2)
; #pragma unroll
;                 for (int c2 = 0; c2 < 2; ++c2) { const f32x4 rp = acc[r2][c2] + ba[c2], ip = acc[r2][c2 + 2] + bx[c2]; const v2u xw = xq[r2][c2];
;                     const float xv[4] = {bf_lo(xw.x), bf_hi(xw.x), bf_lo(xw.y), bf_hi(xw.y)};
; #pragma unroll
;                     for (int j = 0; j < 4; ++j) { const float r = pg8::sigmoidf_(rp[j]), ig = pg8::sigmoidf_(ip[j]);
;                         const float av = __builtin_amdgcn_exp2f(sp[c2][j] * r);
;                         A[r2][c2][j] = av; U[r2][c2][j] = __builtin_amdgcn_sqrtf(fmaxf(__builtin_fmaf(-av, av, 1.0f), 0.0f)) * (ig * xv[j]); } }
	v_rcp_f32_e32 v3, v3
	v_exp_f32_e32 v99, v99
	v_add_f32_e32 v104, 1.0, v109
	v_add_f32_e32 v94, v14, v94
	v_rcp_f32_e32 v104, v104
	v_mul_f32_e32 v94, 0xbfb8aa3b, v94
	v_mul_f32_e32 v3, v134, v3
	v_exp_f32_e32 v94, v94
	v_exp_f32_e32 v98, v3
	global_load_dwordx4 v[154:157], v[38:39], off
	v_add_f32_e32 v99, 1.0, v99
	v_add_f32_e32 v101, v9, v101
	v_rcp_f32_e32 v99, v99
	v_mul_f32_e32 v101, 0xbfb8aa3b, v101
	v_exp_f32_e32 v101, v101
	v_mul_f32_e32 v104, v104, v107
	v_mul_f32_e32 v191, v104, v105
	v_lshlrev_b32_e32 v105, 16, v103
	v_and_b32_e32 v3, 0xffff0000, v103
	v_add_f32_e32 v94, 1.0, v94
	v_fma_f32 v103, -v98, v98, 1.0
	v_add_f32_e32 v95, v15, v95
	v_rcp_f32_e32 v94, v94
	v_max_f32_e32 v103, 0, v103
	v_mul_f32_e32 v95, 0xbfb8aa3b, v95
	v_mul_f32_e32 v99, v135, v99
	v_sqrt_f32_e32 v103, v103
	v_exp_f32_e32 v95, v95
	v_exp_f32_e32 v99, v99
	v_add_f32_e32 v100, v8, v100
	v_add_f32_e32 v101, 1.0, v101
	v_mul_f32_e32 v100, 0xbfb8aa3b, v100
	v_rcp_f32_e32 v101, v101
	v_lshlrev_b32_e32 v104, 16, v102
	v_exp_f32_e32 v100, v100
	v_mul_f32_e32 v94, v94, v104
	v_mul_f32_e32 v94, v94, v103
	v_add_f32_e32 v95, 1.0, v95
	v_fma_f32 v103, -v99, v99, 1.0
	v_add_f32_e32 v97, v17, v97
	v_rcp_f32_e32 v95, v95
	v_lshl_add_u64 v[38:39], v[110:111], 0, s[24:25]
	v_lshl_add_u64 v[148:149], v[38:39], 0, 16
	v_lshlrev_b64 v[150:151], 13, v[148:149]
	v_lshl_add_u64 v[38:39], v[122:123], 0, v[150:151]
	v_subrev_u32_e32 v38, s68, v38
	global_load_dwordx4 v[82:85], v38, s[68:69]
	v_max_f32_e32 v103, 0, v103
	v_mul_f32_e32 v97, 0xbfb8aa3b, v97
	v_mul_f32_e32 v101, v133, v101
	v_sqrt_f32_e32 v103, v103
	v_add_f32_e32 v100, 1.0, v100
	v_exp_f32_e32 v97, v97
	v_exp_f32_e32 v101, v101
	v_rcp_f32_e32 v100, v100
	v_and_b32_e32 v102, 0xffff0000, v102
	v_mul_f32_e32 v95, v95, v102
	v_add_f32_e32 v96, v16, v96
	v_mul_f32_e32 v95, v95, v103
	v_add_f32_e32 v97, 1.0, v97
	v_fma_f32 v103, -v101, v101, 1.0
	v_mul_f32_e32 v96, 0xbfb8aa3b, v96
	global_load_dwordx4 v[78:81], v38, s[68:69] offset:64
	v_mul_f32_e32 v100, v132, v100
	v_rcp_f32_e32 v97, v97
	v_max_f32_e32 v103, 0, v103
	v_exp_f32_e32 v96, v96
	v_exp_f32_e32 v100, v100
	v_sqrt_f32_e32 v103, v103
	v_mul_f32_e32 v3, v97, v3
	v_add_f32_e32 v96, 1.0, v96
	v_fma_f32 v102, -v100, v100, 1.0
	v_mul_f32_e32 v97, v3, v103
	v_add_f32_e32 v3, v10, v90
	v_rcp_f32_e32 v96, v96
	v_max_f32_e32 v102, 0, v102
	v_mul_f32_e32 v3, 0xbfb8aa3b, v3
	v_sqrt_f32_e32 v102, v102
	global_load_dwordx4 v[74:77], v38, s[68:69] offset:128
	v_exp_f32_e32 v3, v3
	v_mul_f32_e32 v96, v96, v105
	v_lshlrev_b32_e32 v90, 16, v4
	v_mul_f32_e32 v96, v96, v102
	v_and_b32_e32 v102, 0xffff0000, v4
	v_add_f32_e32 v3, 1.0, v3
	v_add_f32_e32 v4, v18, v86
	v_rcp_f32_e32 v3, v3
	v_mul_f32_e32 v4, 0xbfb8aa3b, v4
	v_exp_f32_e32 v86, v4
	v_lshlrev_b32_e32 v103, 16, v5
	v_mul_f32_e32 v3, v138, v3
	v_exp_f32_e32 v4, v3
	v_and_b32_e32 v3, 0xffff0000, v5
	v_add_f32_e32 v5, 1.0, v86
	v_rcp_f32_e32 v5, v5
	global_load_dwordx4 v[66:69], v38, s[68:69] offset:192
	v_fma_f32 v86, -v4, v4, 1.0
	v_add_f32_e32 v87, v19, v87
	v_max_f32_e32 v86, 0, v86
	v_mul_f32_e32 v5, v5, v90
	v_add_f32_e32 v90, v11, v91
	v_mul_f32_e32 v90, 0xbfb8aa3b, v90
	v_exp_f32_e32 v90, v90
	v_mul_f32_e32 v87, 0xbfb8aa3b, v87
	v_sqrt_f32_e32 v86, v86
	v_exp_f32_e32 v87, v87
	v_add_f32_e32 v90, 1.0, v90
	v_rcp_f32_e32 v90, v90
	v_mul_f32_e32 v86, v5, v86
	v_add_f32_e32 v5, 1.0, v87
	v_rcp_f32_e32 v87, v5
	global_load_dwordx4 v[58:61], v38, s[68:69] offset:256
	v_mul_f32_e32 v5, v139, v90
	v_add_f32_e32 v90, v12, v92
	v_mul_f32_e32 v90, 0xbfb8aa3b, v90
	v_exp_f32_e32 v90, v90
	v_exp_f32_e32 v5, v5
	v_add_f32_e32 v88, v20, v88
; __device__ __forceinline__ float bf_lo(unsigned w) { return __uint_as_float(w << 16); }
; __device__ __forceinline__ float bf_hi(unsigned w) { return __uint_as_float(w & 0xffff0000u); }
; __device__ __forceinline__ float sigmoidf_(float x) { return fast_rcp(1.0f + fast_exp(-x)); }
; __device__ __forceinline__ void lru_fused(const bf16* XC, const bf16* Wrg_t, const bf16* PROJ, bf16* YL, const float* b_a, const float* b_x, const float* sp8,
;                                           LAS unsigned char* lds, int tid, int lane, int wave, int vcu, int G) {
;     ...
;                 for (int r2 = 0; r2 < 2; ++r2) { const size_t ro = (rown + 16 * r2 + fr) * D, rg = (rown + 16 * r2 + fr) * NIN;
; #pragma unroll
;                     for (int kb = 0; kb < 8; ++kb) af[r2][kb] = *(const bf16x8*)(abase + ro + 32 * kb);
; #pragma unroll
;                     for (int c2 = 0; c2 < 2; ++c2) { xqn[r2][c2] = *(const v2u*)(xbase + ro + 16 * c2); gqn[r2][c2] = *(const v2u*)(gbase + rg + 16 * c2); } } }
;             float A[2][2][4], U[2][2][4];
; #pragma unroll
;             for (int r2 = 0; r2 < 2; ++r2)
; #pragma unroll
;                 for (int c2 = 0; c2 < 2; ++c2) { const f32x4 rp = acc[r2][c2] + ba[c2], ip = acc[r2][c2 + 2] + bx[c2]; const v2u xw = xq[r2][c2];
;                     const float xv[4] = {bf_lo(xw.x), bf_hi(xw.x), bf_lo(xw.y), bf_hi(xw.y)};
; #pragma unroll
;                     for (int j = 0; j < 4; ++j) { const float r = pg8::sigmoidf_(rp[j]), ig = pg8::sigmoidf_(ip[j]);
;                         const float av = __builtin_amdgcn_exp2f(sp[c2][j] * r);
;                         A[r2][c2][j] = av; U[r2][c2][j] = __builtin_amdgcn_sqrtf(fmaxf(__builtin_fmaf(-av, av, 1.0f), 0.0f)) * (ig * xv[j]); } }
;     ...
; #pragma unroll
;             for (int r2 = 0; r2 < 2; ++r2)
; #pragma unroll
;                 for (int c2 = 0; c2 < 2; ++c2)
;                     asm volatile("s_nop 1\n\t" LRU_STEP(1) LRU_STEP(2) LRU_STEP(4) LRU_STEP(8)
;                                  : "+v"(A[r2][c2][0]), "+v"(A[r2][c2][1]), "+v"(A[r2][c2][2]), "+v"(A[r2][c2][3]), "+v"(U[r2][c2][0]), "+v"(U[r2][c2][1]), "+v"(U[r2][c2][2]), "+v"(U[r2][c2][3]));
	v_add_f32_e32 v89, v21, v89
	v_add_f32_e32 v90, 1.0, v90
	v_rcp_f32_e32 v90, v90
	v_fma_f32 v91, -v5, v5, 1.0
	v_max_f32_e32 v91, 0, v91
	v_sqrt_f32_e32 v91, v91
	v_mul_f32_e32 v90, v136, v90
	v_exp_f32_e32 v92, v90
	v_add_f32_e32 v90, v13, v93
	global_load_dwordx4 v[50:53], v38, s[68:69] offset:320
	v_mul_f32_e32 v90, 0xbfb8aa3b, v90
	v_exp_f32_e32 v90, v90
	v_mul_f32_e32 v88, 0xbfb8aa3b, v88
	v_mul_f32_e32 v89, 0xbfb8aa3b, v89
	v_exp_f32_e32 v88, v88
	v_add_f32_e32 v90, 1.0, v90
	v_rcp_f32_e32 v90, v90
	v_exp_f32_e32 v89, v89
	v_mul_f32_e32 v87, v87, v102
	v_mul_f32_e32 v87, v87, v91
	v_mul_f32_e32 v90, v137, v90
	v_exp_f32_e32 v93, v90
	v_fma_f32 v91, -v92, v92, 1.0
	v_max_f32_e32 v91, 0, v91
	v_add_f32_e32 v88, 1.0, v88
	global_load_dwordx4 v[42:45], v38, s[68:69] offset:384
	v_sqrt_f32_e32 v90, v91
	v_add_f32_e32 v89, 1.0, v89
	v_fma_f32 v91, -v93, v93, 1.0
	v_rcp_f32_e32 v88, v88
	v_rcp_f32_e32 v89, v89
	v_max_f32_e32 v91, 0, v91
	v_sqrt_f32_e32 v91, v91
	v_mul_f32_e32 v88, v88, v103
	v_mul_f32_e32 v3, v89, v3
	v_mul_f32_e32 v88, v88, v90
	v_mul_f32_e32 v89, v3, v91
	s_nop 1
	v_fmac_f32_dpp v175, v175, v173 row_shr:1 row_mask:0xf bank_mask:0xf
	v_mul_f32_dpp v173, v173, v173 row_shr:1 row_mask:0xf bank_mask:0xf
	v_fmac_f32_dpp v177, v177, v174 row_shr:1 row_mask:0xf bank_mask:0xf
	v_mul_f32_dpp v174, v174, v174 row_shr:1 row_mask:0xf bank_mask:0xf
	s_nop 0
	global_load_dwordx4 v[38:41], v38, s[68:69] offset:448
	v_fmac_f32_dpp v184, v184, v181 row_shr:1 row_mask:0xf bank_mask:0xf
	v_mul_f32_dpp v181, v181, v181 row_shr:1 row_mask:0xf bank_mask:0xf
	v_fmac_f32_dpp v182, v182, v176 row_shr:1 row_mask:0xf bank_mask:0xf
	v_mul_f32_dpp v176, v176, v176 row_shr:1 row_mask:0xf bank_mask:0xf
	v_fmac_f32_dpp v175, v175, v173 row_shr:2 row_mask:0xf bank_mask:0xf
	v_mul_f32_dpp v173, v173, v173 row_shr:2 row_mask:0xf bank_mask:0xf
	v_fmac_f32_dpp v177, v177, v174 row_shr:2 row_mask:0xf bank_mask:0xf
	v_mul_f32_dpp v174, v174, v174 row_shr:2 row_mask:0xf bank_mask:0xf
	v_fmac_f32_dpp v184, v184, v181 row_shr:2 row_mask:0xf bank_mask:0xf
	v_mul_f32_dpp v181, v181, v181 row_shr:2 row_mask:0xf bank_mask:0xf
	v_fmac_f32_dpp v182, v182, v176 row_shr:2 row_mask:0xf bank_mask:0xf
	v_mul_f32_dpp v176, v176, v176 row_shr:2 row_mask:0xf bank_mask:0xf
	v_fmac_f32_dpp v175, v175, v173 row_shr:4 row_mask:0xf bank_mask:0xf
	v_mul_f32_dpp v173, v173, v173 row_shr:4 row_mask:0xf bank_mask:0xf
	v_fmac_f32_dpp v177, v177, v174 row_shr:4 row_mask:0xf bank_mask:0xf
	v_mad_u64_u32 v[162:163], s[24:25], v148, s13, v[126:127]
	v_mov_b32_e32 v148, v163
	v_mad_u64_u32 v[148:149], s[24:25], v149, s13, v[148:149]
	v_lshl_add_u64 v[150:151], v[124:125], 0, v[150:151]
	v_mov_b32_e32 v163, v148
	v_mul_f32_dpp v174, v174, v174 row_shr:4 row_mask:0xf bank_mask:0xf
	v_fmac_f32_dpp v184, v184, v181 row_shr:4 row_mask:0xf bank_mask:0xf
	v_mul_f32_dpp v181, v181, v181 row_shr:4 row_mask:0xf bank_mask:0xf
	v_fmac_f32_dpp v182, v182, v176 row_shr:4 row_mask:0xf bank_mask:0xf
	v_mul_f32_dpp v176, v176, v176 row_shr:4 row_mask:0xf bank_mask:0xf
	v_fmac_f32_dpp v175, v175, v173 row_shr:8 row_mask:0xf bank_mask:0xf
	v_mul_f32_dpp v173, v173, v173 row_shr:8 row_mask:0xf bank_mask:0xf
	v_fmac_f32_dpp v177, v177, v174 row_shr:8 row_mask:0xf bank_mask:0xf
	v_mul_f32_dpp v174, v174, v174 row_shr:8 row_mask:0xf bank_mask:0xf
	v_fmac_f32_dpp v184, v184, v181 row_shr:8 row_mask:0xf bank_mask:0xf
	v_mul_f32_dpp v181, v181, v181 row_shr:8 row_mask:0xf bank_mask:0xf
	v_fmac_f32_dpp v182, v182, v176 row_shr:8 row_mask:0xf bank_mask:0xf
	v_mul_f32_dpp v176, v176, v176 row_shr:8 row_mask:0xf bank_mask:0xf

; __device__ __forceinline__ void lru_fused(const bf16* XC, const bf16* Wrg_t, const bf16* PROJ, bf16* YL, const float* b_a, const float* b_x, const float* sp8,
;                                           LAS unsigned char* lds, int tid, int lane, int wave, int vcu, int G) {
;     ...
; #pragma unroll
;             for (int r2 = 0; r2 < 2; ++r2)
; #pragma unroll
;                 for (int c2 = 0; c2 < 2; ++c2)
;                     asm volatile("s_nop 1\n\t" LRU_STEP(1) LRU_STEP(2) LRU_STEP(4) LRU_STEP(8)
;                                  : "+v"(A[r2][c2][0]), "+v"(A[r2][c2][1]), "+v"(A[r2][c2][2]), "+v"(A[r2][c2][3]), "+v"(U[r2][c2][0]), "+v"(U[r2][c2][1]), "+v"(U[r2][c2][2]), "+v"(U[r2][c2][3]));
;     ...
;             const int l15 = (lane & 48) | 15;
; #pragma unroll
;             for (int c2 = 0; c2 < 2; ++c2)
; #pragma unroll
;                 for (int j = 0; j < 4; ++j) { const float a15 = __shfl(A[0][c2][j], l15), u15 = __shfl(U[0][c2][j], l15);
	ds_bpermute_b32 v90, v172, v173
	ds_bpermute_b32 v102, v172, v175
	s_nop 0
	global_load_dwordx4 v[160:163], v[162:163], off
	ds_bpermute_b32 v103, v172, v177
	ds_bpermute_b32 v91, v172, v174
	ds_bpermute_b32 v104, v172, v184
	ds_bpermute_b32 v105, v172, v182
	s_nop 1
	v_fmac_f32_dpp v186, v186, v183 row_shr:1 row_mask:0xf bank_mask:0xf
	v_mul_f32_dpp v183, v183, v183 row_shr:1 row_mask:0xf bank_mask:0xf
	v_fmac_f32_dpp v188, v188, v185 row_shr:1 row_mask:0xf bank_mask:0xf
	v_mul_f32_dpp v185, v185, v185 row_shr:1 row_mask:0xf bank_mask:0xf
	v_fmac_f32_dpp v191, v191, v189 row_shr:1 row_mask:0xf bank_mask:0xf
	v_mul_f32_dpp v189, v189, v189 row_shr:1 row_mask:0xf bank_mask:0xf
	v_fmac_f32_dpp v190, v190, v187 row_shr:1 row_mask:0xf bank_mask:0xf
	v_mul_f32_dpp v187, v187, v187 row_shr:1 row_mask:0xf bank_mask:0xf
	v_fmac_f32_dpp v186, v186, v183 row_shr:2 row_mask:0xf bank_mask:0xf
	v_mul_f32_dpp v183, v183, v183 row_shr:2 row_mask:0xf bank_mask:0xf
	v_fmac_f32_dpp v188, v188, v185 row_shr:2 row_mask:0xf bank_mask:0xf
	v_mul_f32_dpp v185, v185, v185 row_shr:2 row_mask:0xf bank_mask:0xf
	v_fmac_f32_dpp v191, v191, v189 row_shr:2 row_mask:0xf bank_mask:0xf
	v_mul_f32_dpp v189, v189, v189 row_shr:2 row_mask:0xf bank_mask:0xf
	v_fmac_f32_dpp v190, v190, v187 row_shr:2 row_mask:0xf bank_mask:0xf
	v_mul_f32_dpp v187, v187, v187 row_shr:2 row_mask:0xf bank_mask:0xf
	v_fmac_f32_dpp v186, v186, v183 row_shr:4 row_mask:0xf bank_mask:0xf
	v_mul_f32_dpp v183, v183, v183 row_shr:4 row_mask:0xf bank_mask:0xf
	v_fmac_f32_dpp v188, v188, v185 row_shr:4 row_mask:0xf bank_mask:0xf
	v_mul_f32_dpp v185, v185, v185 row_shr:4 row_mask:0xf bank_mask:0xf
	v_fmac_f32_dpp v191, v191, v189 row_shr:4 row_mask:0xf bank_mask:0xf
	v_mul_f32_dpp v189, v189, v189 row_shr:4 row_mask:0xf bank_mask:0xf
	v_fmac_f32_dpp v190, v190, v187 row_shr:4 row_mask:0xf bank_mask:0xf
	v_mul_f32_dpp v187, v187, v187 row_shr:4 row_mask:0xf bank_mask:0xf
	v_fmac_f32_dpp v186, v186, v183 row_shr:8 row_mask:0xf bank_mask:0xf
	v_mul_f32_dpp v183, v183, v183 row_shr:8 row_mask:0xf bank_mask:0xf
	v_fmac_f32_dpp v188, v188, v185 row_shr:8 row_mask:0xf bank_mask:0xf
	v_mul_f32_dpp v185, v185, v185 row_shr:8 row_mask:0xf bank_mask:0xf
	v_fmac_f32_dpp v191, v191, v189 row_shr:8 row_mask:0xf bank_mask:0xf
	v_mul_f32_dpp v189, v189, v189 row_shr:8 row_mask:0xf bank_mask:0xf
	v_fmac_f32_dpp v190, v190, v187 row_shr:8 row_mask:0xf bank_mask:0xf
	v_mul_f32_dpp v187, v187, v187 row_shr:8 row_mask:0xf bank_mask:0xf

; __device__ __forceinline__ void lru_fused(const bf16* XC, const bf16* Wrg_t, const bf16* PROJ, bf16* YL, const float* b_a, const float* b_x, const float* sp8,
;                                           LAS unsigned char* lds, int tid, int lane, int wave, int vcu, int G) {
;     ...
; #pragma unroll
;             for (int r2 = 0; r2 < 2; ++r2)
; #pragma unroll
;                 for (int c2 = 0; c2 < 2; ++c2)
;                     asm volatile("s_nop 1\n\t" LRU_STEP(1) LRU_STEP(2) LRU_STEP(4) LRU_STEP(8)
;                                  : "+v"(A[r2][c2][0]), "+v"(A[r2][c2][1]), "+v"(A[r2][c2][2]), "+v"(A[r2][c2][3]), "+v"(U[r2][c2][0]), "+v"(U[r2][c2][1]), "+v"(U[r2][c2][2]), "+v"(U[r2][c2][3]));
	s_nop 1
	v_fmac_f32_dpp v94, v94, v98 row_shr:1 row_mask:0xf bank_mask:0xf
	v_mul_f32_dpp v98, v98, v98 row_shr:1 row_mask:0xf bank_mask:0xf
	v_fmac_f32_dpp v95, v95, v99 row_shr:1 row_mask:0xf bank_mask:0xf
	v_mul_f32_dpp v99, v99, v99 row_shr:1 row_mask:0xf bank_mask:0xf
	v_fmac_f32_dpp v96, v96, v100 row_shr:1 row_mask:0xf bank_mask:0xf
	v_mul_f32_dpp v100, v100, v100 row_shr:1 row_mask:0xf bank_mask:0xf
	v_fmac_f32_dpp v97, v97, v101 row_shr:1 row_mask:0xf bank_mask:0xf
	v_mul_f32_dpp v101, v101, v101 row_shr:1 row_mask:0xf bank_mask:0xf
	v_fmac_f32_dpp v94, v94, v98 row_shr:2 row_mask:0xf bank_mask:0xf
	v_mul_f32_dpp v98, v98, v98 row_shr:2 row_mask:0xf bank_mask:0xf
	v_fmac_f32_dpp v95, v95, v99 row_shr:2 row_mask:0xf bank_mask:0xf
	v_mul_f32_dpp v99, v99, v99 row_shr:2 row_mask:0xf bank_mask:0xf
	v_fmac_f32_dpp v96, v96, v100 row_shr:2 row_mask:0xf bank_mask:0xf
	v_mul_f32_dpp v100, v100, v100 row_shr:2 row_mask:0xf bank_mask:0xf
	v_fmac_f32_dpp v97, v97, v101 row_shr:2 row_mask:0xf bank_mask:0xf
	v_mul_f32_dpp v101, v101, v101 row_shr:2 row_mask:0xf bank_mask:0xf
	v_fmac_f32_dpp v94, v94, v98 row_shr:4 row_mask:0xf bank_mask:0xf
	v_mul_f32_dpp v98, v98, v98 row_shr:4 row_mask:0xf bank_mask:0xf
	v_fmac_f32_dpp v95, v95, v99 row_shr:4 row_mask:0xf bank_mask:0xf
	v_mul_f32_dpp v99, v99, v99 row_shr:4 row_mask:0xf bank_mask:0xf
	v_fmac_f32_dpp v96, v96, v100 row_shr:4 row_mask:0xf bank_mask:0xf
	v_mul_f32_dpp v100, v100, v100 row_shr:4 row_mask:0xf bank_mask:0xf
	v_fmac_f32_dpp v97, v97, v101 row_shr:4 row_mask:0xf bank_mask:0xf
	v_mul_f32_dpp v101, v101, v101 row_shr:4 row_mask:0xf bank_mask:0xf
	v_fmac_f32_dpp v94, v94, v98 row_shr:8 row_mask:0xf bank_mask:0xf
	v_mul_f32_dpp v98, v98, v98 row_shr:8 row_mask:0xf bank_mask:0xf
	v_fmac_f32_dpp v95, v95, v99 row_shr:8 row_mask:0xf bank_mask:0xf
	v_mul_f32_dpp v99, v99, v99 row_shr:8 row_mask:0xf bank_mask:0xf
	v_fmac_f32_dpp v96, v96, v100 row_shr:8 row_mask:0xf bank_mask:0xf
	v_mul_f32_dpp v100, v100, v100 row_shr:8 row_mask:0xf bank_mask:0xf
	v_fmac_f32_dpp v97, v97, v101 row_shr:8 row_mask:0xf bank_mask:0xf
	v_mul_f32_dpp v101, v101, v101 row_shr:8 row_mask:0xf bank_mask:0xf

; __device__ __forceinline__ void lru_fused(const bf16* XC, const bf16* Wrg_t, const bf16* PROJ, bf16* YL, const float* b_a, const float* b_x, const float* sp8,
;                                           LAS unsigned char* lds, int tid, int lane, int wave, int vcu, int G) {
;     ...
;             for (int r2 = 0; r2 < 2; ++r2)
; #pragma unroll
;                 for (int c2 = 0; c2 < 2; ++c2)
;                     asm volatile("s_nop 1\n\t" LRU_STEP(1) LRU_STEP(2) LRU_STEP(4) LRU_STEP(8)
;                                  : "+v"(A[r2][c2][0]), "+v"(A[r2][c2][1]), "+v"(A[r2][c2][2]), "+v"(A[r2][c2][3]), "+v"(U[r2][c2][0]), "+v"(U[r2][c2][1]), "+v"(U[r2][c2][2]), "+v"(U[r2][c2][3]));
;     ...
;             const int l15 = (lane & 48) | 15;
; #pragma unroll
;             for (int c2 = 0; c2 < 2; ++c2)
; #pragma unroll
;                 for (int j = 0; j < 4; ++j) { const float a15 = __shfl(A[0][c2][j], l15), u15 = __shfl(U[0][c2][j], l15);
;                     U[1][c2][j] = A[1][c2][j] * u15 + U[1][c2][j]; A[1][c2][j] = A[1][c2][j] * a15; }
	ds_bpermute_b32 v106, v172, v189
	s_waitcnt lgkmcnt(4)
	v_pk_fma_f32 v[94:95], v[98:99], v[102:103], v[94:95]
	s_waitcnt lgkmcnt(3)
	v_pk_mul_f32 v[98:99], v[98:99], v[90:91]
	ds_bpermute_b32 v90, v172, v181
	ds_bpermute_b32 v91, v172, v176
	s_waitcnt lgkmcnt(3)
	v_pk_fma_f32 v[96:97], v[100:101], v[104:105], v[96:97]
	ds_bpermute_b32 v102, v172, v183
	ds_bpermute_b32 v104, v172, v186
	ds_bpermute_b32 v103, v172, v185
	ds_bpermute_b32 v105, v172, v188
	ds_bpermute_b32 v108, v172, v191
	ds_bpermute_b32 v109, v172, v190
	ds_bpermute_b32 v107, v172, v187
	s_and_b32 s24, s22, 1
	s_nop 1
	v_fmac_f32_dpp v86, v86, v4 row_shr:1 row_mask:0xf bank_mask:0xf
	v_mul_f32_dpp v4, v4, v4 row_shr:1 row_mask:0xf bank_mask:0xf
	v_fmac_f32_dpp v87, v87, v5 row_shr:1 row_mask:0xf bank_mask:0xf
	v_mul_f32_dpp v5, v5, v5 row_shr:1 row_mask:0xf bank_mask:0xf
	v_fmac_f32_dpp v88, v88, v92 row_shr:1 row_mask:0xf bank_mask:0xf
	v_mul_f32_dpp v92, v92, v92 row_shr:1 row_mask:0xf bank_mask:0xf
	v_fmac_f32_dpp v89, v89, v93 row_shr:1 row_mask:0xf bank_mask:0xf
	v_mul_f32_dpp v93, v93, v93 row_shr:1 row_mask:0xf bank_mask:0xf
	v_fmac_f32_dpp v86, v86, v4 row_shr:2 row_mask:0xf bank_mask:0xf
	v_mul_f32_dpp v4, v4, v4 row_shr:2 row_mask:0xf bank_mask:0xf
	v_fmac_f32_dpp v87, v87, v5 row_shr:2 row_mask:0xf bank_mask:0xf
	v_mul_f32_dpp v5, v5, v5 row_shr:2 row_mask:0xf bank_mask:0xf
	v_fmac_f32_dpp v88, v88, v92 row_shr:2 row_mask:0xf bank_mask:0xf
	v_mul_f32_dpp v92, v92, v92 row_shr:2 row_mask:0xf bank_mask:0xf
	v_fmac_f32_dpp v89, v89, v93 row_shr:2 row_mask:0xf bank_mask:0xf
	v_mul_f32_dpp v93, v93, v93 row_shr:2 row_mask:0xf bank_mask:0xf
	v_fmac_f32_dpp v86, v86, v4 row_shr:4 row_mask:0xf bank_mask:0xf
	v_mul_f32_dpp v4, v4, v4 row_shr:4 row_mask:0xf bank_mask:0xf
	v_fmac_f32_dpp v87, v87, v5 row_shr:4 row_mask:0xf bank_mask:0xf
	v_mul_f32_dpp v5, v5, v5 row_shr:4 row_mask:0xf bank_mask:0xf
	v_fmac_f32_dpp v88, v88, v92 row_shr:4 row_mask:0xf bank_mask:0xf
	v_mul_f32_dpp v92, v92, v92 row_shr:4 row_mask:0xf bank_mask:0xf
	v_fmac_f32_dpp v89, v89, v93 row_shr:4 row_mask:0xf bank_mask:0xf
	v_mul_f32_dpp v93, v93, v93 row_shr:4 row_mask:0xf bank_mask:0xf
	v_fmac_f32_dpp v86, v86, v4 row_shr:8 row_mask:0xf bank_mask:0xf
	v_mul_f32_dpp v4, v4, v4 row_shr:8 row_mask:0xf bank_mask:0xf
	v_fmac_f32_dpp v87, v87, v5 row_shr:8 row_mask:0xf bank_mask:0xf
	v_mul_f32_dpp v5, v5, v5 row_shr:8 row_mask:0xf bank_mask:0xf
	v_fmac_f32_dpp v88, v88, v92 row_shr:8 row_mask:0xf bank_mask:0xf
	v_mul_f32_dpp v92, v92, v92 row_shr:8 row_mask:0xf bank_mask:0xf
	v_fmac_f32_dpp v89, v89, v93 row_shr:8 row_mask:0xf bank_mask:0xf
	v_mul_f32_dpp v93, v93, v93 row_shr:8 row_mask:0xf bank_mask:0xf

; #define LAS __attribute__((address_space(3)))
; __device__ __forceinline__ void lru_fused(const bf16* XC, const bf16* Wrg_t, const bf16* PROJ, bf16* YL, const float* b_a, const float* b_x, const float* sp8,
;                                           LAS unsigned char* lds, int tid, int lane, int wave, int vcu, int G) {
;     ...
;             const int l15 = (lane & 48) | 15;
; #pragma unroll
;             for (int c2 = 0; c2 < 2; ++c2)
; #pragma unroll
;                 for (int j = 0; j < 4; ++j) { const float a15 = __shfl(A[0][c2][j], l15), u15 = __shfl(U[0][c2][j], l15);
;                     U[1][c2][j] = A[1][c2][j] * u15 + U[1][c2][j]; A[1][c2][j] = A[1][c2][j] * a15; }
;             LAS float* xp = xch + (i & 1) * 512;
;             if (fr == 15) {
; #pragma unroll
;                 for (int c2 = 0; c2 < 2; ++c2) { *(LAS f32x4*)(xp + wave * 32 + 16 * c2 + 4 * fq) = (f32x4){A[1][c2][0], A[1][c2][1], A[1][c2][2], A[1][c2][3]};
;                     *(LAS f32x4*)(xp + 256 + wave * 32 + 16 * c2 + 4 * fq) = (f32x4){U[1][c2][0], U[1][c2][1], U[1][c2][2], U[1][c2][3]}; } }
	s_lshl_b32 s23, s24, 11
	s_waitcnt lgkmcnt(7)
	v_pk_mul_f32 v[100:101], v[100:101], v[90:91]
	s_waitcnt lgkmcnt(3)
	v_pk_fma_f32 v[86:87], v[4:5], v[104:105], v[86:87]
	v_pk_mul_f32 v[90:91], v[4:5], v[102:103]
	s_waitcnt lgkmcnt(1)
	v_pk_fma_f32 v[88:89], v[92:93], v[108:109], v[88:89]
	s_waitcnt lgkmcnt(0)
	v_pk_mul_f32 v[92:93], v[92:93], v[106:107]
	s_add_i32 s23, s23, 0
	s_and_saveexec_b64 s[66:67], s[2:3]
	s_cbranch_execz .LBB0_458
	s_lshl_b32 s25, s6, 2
	s_add_i32 s25, s23, s25
	v_lshl_add_u32 v3, v165, 2, s25
	ds_write_b128 v3, v[98:101] offset:36864
	ds_write_b128 v3, v[94:97] offset:37888
	ds_write_b128 v3, v[90:93] offset:36928
	ds_write_b128 v3, v[86:89] offset:37952
